# conv+GEGLU phase walks its items from the last row block to the first (most recently written up-GEMM rows first)
# speedup vs baseline: 1.0058x; 1.0058x over previous
.LBB0_1004:
	s_or_b64 exec, exec, s[0:1]
	s_mov_b64 s[0:1], s[4:5]
	s_waitcnt lgkmcnt(0)
	s_barrier
	global_load_dwordx2 v[2:3], v1, s[0:1] offset:136
	s_mov_b64 s[0:1], s[4:5]
	global_load_dwordx2 v[4:5], v1, s[0:1] offset:144
	v_mov_b32_e32 v0, v148
	v_readlane_b32 s0, v253, 6
	s_nop 1
	v_add_u32_e32 v128, s0, v0
	v_sub_u32_e32 v128, 0x56abf, v128
	s_mov_b32 s0, 0x56ac0
	v_cmp_le_i32_e32 vcc, 0, v128
	s_and_saveexec_b64 s[8:9], vcc
	s_cbranch_execz .LBB0_1013
	v_readlane_b32 s0, v255, 24
	v_readlane_b32 s1, v255, 25
	s_mul_i32 s14, s0, 0x20400
	s_mul_i32 s0, s0, 0xac00
	s_mov_b32 s1, s15
	s_waitcnt vmcnt(1)
	v_lshl_add_u64 v[92:93], v[2:3], 0, s[14:15]
	s_waitcnt vmcnt(0)
	v_lshl_add_u64 v[94:95], v[4:5], 0, s[0:1]
	s_mov_b64 s[26:27], 0

.LBB0_1011:
	v_lshl_add_u64 v[100:101], v[96:97], 0, s[28:29]
	v_add_co_u32_e32 v84, vcc, 0x198a0000, v100
	s_waitcnt vmcnt(1)
	v_lshlrev_b32_e32 v98, 16, v68
	v_addc_co_u32_e32 v85, vcc, 0, v101, vcc
	global_load_dwordx4 v[88:91], v[84:85], off offset:512
	v_add_co_u32_e32 v84, vcc, 0x198a2000, v100
	v_and_b32_e32 v99, 0xffff0000, v68
	s_nop 0
	v_addc_co_u32_e32 v85, vcc, 0, v101, vcc
	global_load_dwordx4 v[84:87], v[84:85], off offset:3328
	v_pk_fma_f32 v[98:99], v[8:9], v[98:99], v[32:33]
	s_waitcnt vmcnt(2)
	v_lshlrev_b32_e32 v104, 16, v80
	v_and_b32_e32 v105, 0xffff0000, v80
	v_pk_fma_f32 v[98:99], v[12:13], v[104:105], v[98:99]
	v_lshlrev_b32_e32 v106, 16, v76
	v_and_b32_e32 v107, 0xffff0000, v76
	s_mov_b32 s0, 0xbf3a00e3
	v_lshlrev_b32_e32 v68, 16, v69
	v_and_b32_e32 v69, 0xffff0000, v69
	s_add_u32 s28, s28, 0x15800
	s_addc_u32 s29, s29, 0
	s_cmp_eq_u32 s28, 0x56000
	s_waitcnt vmcnt(1)
	v_lshlrev_b32_e32 v102, 16, v88
	v_and_b32_e32 v103, 0xffff0000, v88
	v_pk_fma_f32 v[108:109], v[20:21], v[102:103], v[98:99]
	v_lshlrev_b32_e32 v98, 16, v72
	v_and_b32_e32 v99, 0xffff0000, v72
	v_pk_fma_f32 v[98:99], v[36:37], v[98:99], v[60:61]
	s_waitcnt vmcnt(0)
	v_lshlrev_b32_e32 v112, 16, v84
	v_pk_fma_f32 v[98:99], v[44:45], v[106:107], v[98:99]
	v_and_b32_e32 v113, 0xffff0000, v84
	v_pk_fma_f32 v[110:111], v[52:53], v[112:113], v[98:99]
	v_and_b32_e32 v99, 0x7fffffff, v109
	v_and_b32_e32 v98, 0x7fffffff, v108
	v_pk_fma_f32 v[98:99], v[98:99], s[10:11], 1.0 op_sel_hi:[1,0,0]
	v_cmp_gt_f32_e32 vcc, 0, v108
	v_rcp_f32_e32 v114, v98
	v_rcp_f32_e32 v115, v99
	v_mov_b64_e32 v[98:99], s[0:1]
	v_cmp_gt_f32_e64 s[0:1], 0, v109
	v_lshlrev_b32_e32 v80, 16, v89
	v_pk_fma_f32 v[116:117], v[114:115], s[56:57], v[98:99] op_sel_hi:[1,0,0]
	v_lshlrev_b32_e32 v72, 16, v73
	v_pk_fma_f32 v[116:117], v[114:115], v[116:117], s[58:59] op_sel_hi:[1,1,0]
	v_and_b32_e32 v73, 0xffff0000, v73
	v_pk_fma_f32 v[116:117], v[114:115], v[116:117], s[20:21] op_sel_hi:[1,1,0]
	v_lshlrev_b32_e32 v76, 16, v85
	v_pk_fma_f32 v[116:117], v[114:115], v[116:117], s[46:47] op_sel_hi:[1,1,0]
	s_nop 0
	v_pk_mul_f32 v[114:115], v[114:115], v[116:117]
	v_pk_mul_f32 v[116:117], v[108:109], v[108:109]
	s_nop 0
	v_pk_mul_f32 v[116:117], v[116:117], s[62:63] op_sel_hi:[1,0]
	s_nop 0
	v_exp_f32_e32 v116, v116
	v_exp_f32_e32 v117, v117
	s_nop 0
	v_pk_mul_f32 v[114:115], v[116:117], v[114:115]
	s_nop 0
	v_pk_mul_f32 v[116:117], v[108:109], v[114:115]
	v_pk_fma_f32 v[114:115], v[108:109], v[114:115], v[108:109] neg_lo:[1,0,0] neg_hi:[1,0,0]
	s_nop 0
	v_cndmask_b32_e64 v109, v115, v117, s[0:1]
	v_cndmask_b32_e32 v108, v114, v116, vcc
	v_pk_mul_f32 v[108:109], v[110:111], v[108:109]
	v_pk_fma_f32 v[110:111], v[10:11], v[68:69], v[34:35]
	v_lshlrev_b32_e32 v68, 16, v81
	v_and_b32_e32 v69, 0xffff0000, v81
	v_pk_fma_f32 v[110:111], v[14:15], v[68:69], v[110:111]
	v_and_b32_e32 v81, 0xffff0000, v89
	v_pk_fma_f32 v[88:89], v[22:23], v[80:81], v[110:111]
	v_pk_fma_f32 v[110:111], v[38:39], v[72:73], v[62:63]
	v_lshlrev_b32_e32 v72, 16, v77
	v_and_b32_e32 v73, 0xffff0000, v77
	v_pk_fma_f32 v[110:111], v[46:47], v[72:73], v[110:111]
	v_and_b32_e32 v77, 0xffff0000, v85
	v_pk_fma_f32 v[84:85], v[54:55], v[76:77], v[110:111]
	v_and_b32_e32 v111, 0x7fffffff, v89
	v_and_b32_e32 v110, 0x7fffffff, v88
	v_pk_fma_f32 v[110:111], v[110:111], s[10:11], 1.0 op_sel_hi:[1,0,0]
	v_cmp_gt_f32_e32 vcc, 0, v88
	v_rcp_f32_e32 v110, v110
	v_rcp_f32_e32 v111, v111
	v_cmp_gt_f32_e64 s[0:1], 0, v89
	v_cvt_pk_bf16_f32 v108, v108, v109
	v_pk_fma_f32 v[68:69], v[10:11], v[68:69], v[34:35]
	v_pk_fma_f32 v[114:115], v[110:111], s[56:57], v[98:99] op_sel_hi:[1,0,0]
	v_pk_fma_f32 v[68:69], v[14:15], v[80:81], v[68:69]
	v_pk_fma_f32 v[114:115], v[110:111], v[114:115], s[58:59] op_sel_hi:[1,1,0]
	v_pk_fma_f32 v[72:73], v[38:39], v[72:73], v[62:63]
	v_pk_fma_f32 v[114:115], v[110:111], v[114:115], s[20:21] op_sel_hi:[1,1,0]
	v_pk_fma_f32 v[72:73], v[46:47], v[76:77], v[72:73]
	v_pk_fma_f32 v[114:115], v[110:111], v[114:115], s[46:47] op_sel_hi:[1,1,0]
	v_pk_fma_f32 v[80:81], v[10:11], v[80:81], v[34:35]
	v_pk_mul_f32 v[110:111], v[110:111], v[114:115]
	v_pk_mul_f32 v[114:115], v[88:89], v[88:89]
	v_pk_fma_f32 v[76:77], v[38:39], v[76:77], v[62:63]
	v_pk_mul_f32 v[114:115], v[114:115], s[62:63] op_sel_hi:[1,0]
	s_nop 0
	v_exp_f32_e32 v114, v114
	v_exp_f32_e32 v115, v115
	s_nop 0
	v_pk_mul_f32 v[110:111], v[114:115], v[110:111]
	s_nop 0
	v_pk_mul_f32 v[114:115], v[88:89], v[110:111]
	v_pk_fma_f32 v[110:111], v[88:89], v[110:111], v[88:89] neg_lo:[1,0,0] neg_hi:[1,0,0]
	s_nop 0
	v_cndmask_b32_e64 v89, v111, v115, s[0:1]
	v_cndmask_b32_e32 v88, v110, v114, vcc
	v_pk_mul_f32 v[110:111], v[84:85], v[88:89]
	v_lshlrev_b32_e32 v84, 16, v70
	v_and_b32_e32 v85, 0xffff0000, v70
	v_pk_fma_f32 v[88:89], v[4:5], v[84:85], v[28:29]
	v_lshlrev_b32_e32 v84, 16, v82
	v_and_b32_e32 v85, 0xffff0000, v82
	v_pk_fma_f32 v[88:89], v[16:17], v[84:85], v[88:89]
	v_lshlrev_b32_e32 v114, 16, v90
	v_and_b32_e32 v115, 0xffff0000, v90
	v_pk_fma_f32 v[118:119], v[24:25], v[114:115], v[88:89]
	v_lshlrev_b32_e32 v88, 16, v74
	v_and_b32_e32 v123, 0x7fffffff, v119
	v_and_b32_e32 v122, 0x7fffffff, v118
	v_pk_fma_f32 v[122:123], v[122:123], s[10:11], 1.0 op_sel_hi:[1,0,0]
	v_and_b32_e32 v89, 0xffff0000, v74
	v_rcp_f32_e32 v122, v122
	v_rcp_f32_e32 v123, v123
	v_pk_fma_f32 v[116:117], v[40:41], v[88:89], v[64:65]
	v_lshlrev_b32_e32 v88, 16, v78
	v_and_b32_e32 v89, 0xffff0000, v78
	v_pk_fma_f32 v[124:125], v[122:123], s[56:57], v[98:99] op_sel_hi:[1,0,0]
	v_pk_fma_f32 v[120:121], v[48:49], v[88:89], v[116:117]
	v_pk_fma_f32 v[124:125], v[122:123], v[124:125], s[58:59] op_sel_hi:[1,1,0]
	v_lshlrev_b32_e32 v116, 16, v86
	v_pk_fma_f32 v[124:125], v[122:123], v[124:125], s[20:21] op_sel_hi:[1,1,0]
	v_and_b32_e32 v117, 0xffff0000, v86
	v_pk_fma_f32 v[124:125], v[122:123], v[124:125], s[46:47] op_sel_hi:[1,1,0]
	v_cmp_gt_f32_e32 vcc, 0, v118
	v_pk_mul_f32 v[122:123], v[122:123], v[124:125]
	v_pk_mul_f32 v[124:125], v[118:119], v[118:119]
	v_cmp_gt_f32_e64 s[0:1], 0, v119
	v_pk_mul_f32 v[124:125], v[124:125], s[62:63] op_sel_hi:[1,0]
	v_pk_fma_f32 v[120:121], v[56:57], v[116:117], v[120:121]
	v_exp_f32_e32 v124, v124
	v_exp_f32_e32 v125, v125
	v_lshlrev_b32_e32 v70, 16, v71
	v_and_b32_e32 v71, 0xffff0000, v71
	v_lshlrev_b32_e32 v82, 16, v91
	v_pk_mul_f32 v[122:123], v[124:125], v[122:123]
	v_lshlrev_b32_e32 v74, 16, v75
	v_pk_mul_f32 v[124:125], v[118:119], v[122:123]
	v_pk_fma_f32 v[122:123], v[118:119], v[122:123], v[118:119] neg_lo:[1,0,0] neg_hi:[1,0,0]
	v_and_b32_e32 v75, 0xffff0000, v75
	v_cndmask_b32_e64 v119, v123, v125, s[0:1]
	v_cndmask_b32_e32 v118, v122, v124, vcc
	v_pk_mul_f32 v[118:119], v[120:121], v[118:119]
	v_pk_fma_f32 v[120:121], v[6:7], v[70:71], v[30:31]
	v_lshlrev_b32_e32 v70, 16, v83
	v_and_b32_e32 v71, 0xffff0000, v83
	v_pk_fma_f32 v[120:121], v[18:19], v[70:71], v[120:121]
	v_and_b32_e32 v83, 0xffff0000, v91
	v_pk_fma_f32 v[90:91], v[26:27], v[82:83], v[120:121]
	v_pk_fma_f32 v[120:121], v[42:43], v[74:75], v[66:67]
	v_lshlrev_b32_e32 v74, 16, v79
	v_and_b32_e32 v75, 0xffff0000, v79
	v_pk_fma_f32 v[120:121], v[50:51], v[74:75], v[120:121]
	v_lshlrev_b32_e32 v78, 16, v87
	v_and_b32_e32 v79, 0xffff0000, v87
	v_pk_fma_f32 v[86:87], v[58:59], v[78:79], v[120:121]
	v_and_b32_e32 v121, 0x7fffffff, v91
	v_and_b32_e32 v120, 0x7fffffff, v90
	v_pk_fma_f32 v[120:121], v[120:121], s[10:11], 1.0 op_sel_hi:[1,0,0]
	v_cmp_gt_f32_e32 vcc, 0, v90
	v_rcp_f32_e32 v120, v120
	v_rcp_f32_e32 v121, v121
	v_cmp_gt_f32_e64 s[0:1], 0, v91
	v_cvt_pk_bf16_f32 v109, v110, v111
	v_cvt_pk_bf16_f32 v110, v118, v119
	v_pk_fma_f32 v[122:123], v[120:121], s[56:57], v[98:99] op_sel_hi:[1,0,0]
	s_nop 0
	v_pk_fma_f32 v[122:123], v[120:121], v[122:123], s[58:59] op_sel_hi:[1,1,0]
	s_nop 0
	v_pk_fma_f32 v[122:123], v[120:121], v[122:123], s[20:21] op_sel_hi:[1,1,0]
	s_nop 0
	v_pk_fma_f32 v[122:123], v[120:121], v[122:123], s[46:47] op_sel_hi:[1,1,0]
	s_nop 0
	v_pk_mul_f32 v[120:121], v[120:121], v[122:123]
	v_pk_mul_f32 v[122:123], v[90:91], v[90:91]
	s_nop 0
	v_pk_mul_f32 v[122:123], v[122:123], s[62:63] op_sel_hi:[1,0]
	s_nop 0
	v_exp_f32_e32 v122, v122
	v_exp_f32_e32 v123, v123
	s_nop 0
	v_pk_mul_f32 v[120:121], v[122:123], v[120:121]
	s_nop 0
	v_pk_mul_f32 v[122:123], v[90:91], v[120:121]
	v_pk_fma_f32 v[120:121], v[90:91], v[120:121], v[90:91] neg_lo:[1,0,0] neg_hi:[1,0,0]
	s_nop 0
	v_cndmask_b32_e64 v91, v121, v123, s[0:1]
	v_cndmask_b32_e32 v90, v120, v122, vcc
	v_pk_mul_f32 v[86:87], v[86:87], v[90:91]
	s_mov_b64 s[0:1], s[54:55]
	v_cvt_pk_bf16_f32 v111, v86, v87
	v_add_u32_e32 v90, -3, v0
	v_mov_b64_e32 v[86:87], s[0:1]
	v_mad_i64_i32 v[86:87], s[0:1], v90, s59, v[86:87]
	v_lshl_add_u64 v[86:87], v[86:87], 0, v[2:3]
	v_add_co_u32_e32 v86, vcc, s73, v86
	s_mov_b32 s0, 0x198a5000
	s_nop 0
	v_addc_co_u32_e32 v87, vcc, 0, v87, vcc
	global_store_dwordx4 v[86:87], v[108:111], off offset:512
	v_add_co_u32_e32 v86, vcc, s0, v100
	s_mov_b32 s0, 0x198a8000
	s_nop 0
	v_addc_co_u32_e32 v87, vcc, 0, v101, vcc
	global_load_dwordx4 v[118:121], v[86:87], off offset:2048
	v_add_co_u32_e32 v86, vcc, s0, v100
	v_pk_fma_f32 v[90:91], v[36:37], v[106:107], v[60:61]
	s_nop 0
	v_addc_co_u32_e32 v87, vcc, 0, v101, vcc
	global_load_dwordx4 v[122:125], v[86:87], off offset:768
	v_pk_fma_f32 v[86:87], v[8:9], v[104:105], v[32:33]
	v_pk_fma_f32 v[90:91], v[44:45], v[112:113], v[90:91]
	v_pk_fma_f32 v[86:87], v[12:13], v[102:103], v[86:87]
	v_pk_fma_f32 v[102:103], v[8:9], v[102:103], v[32:33]
	v_pk_fma_f32 v[112:113], v[36:37], v[112:113], v[60:61]
	s_waitcnt vmcnt(1)
	v_lshlrev_b32_e32 v110, 16, v118
	v_and_b32_e32 v111, 0xffff0000, v118
	v_pk_fma_f32 v[86:87], v[20:21], v[110:111], v[86:87]
	v_pk_fma_f32 v[102:103], v[12:13], v[110:111], v[102:103]
	v_and_b32_e32 v105, 0x7fffffff, v87
	v_and_b32_e32 v104, 0x7fffffff, v86
	v_pk_fma_f32 v[104:105], v[104:105], s[10:11], 1.0 op_sel_hi:[1,0,0]
	v_cmp_gt_f32_e32 vcc, 0, v86
	v_rcp_f32_e32 v104, v104
	v_rcp_f32_e32 v105, v105
	v_cmp_gt_f32_e64 s[0:1], 0, v87
	s_waitcnt vmcnt(0)
	v_lshlrev_b32_e32 v108, 16, v122
	v_and_b32_e32 v109, 0xffff0000, v122
	v_pk_fma_f32 v[106:107], v[104:105], s[56:57], v[98:99] op_sel_hi:[1,0,0]
	v_pk_fma_f32 v[90:91], v[52:53], v[108:109], v[90:91]
	v_pk_fma_f32 v[106:107], v[104:105], v[106:107], s[58:59] op_sel_hi:[1,1,0]
	v_pk_fma_f32 v[112:113], v[44:45], v[108:109], v[112:113]
	v_pk_fma_f32 v[106:107], v[104:105], v[106:107], s[20:21] op_sel_hi:[1,1,0]
	v_pk_fma_f32 v[108:109], v[36:37], v[108:109], v[60:61]
	v_pk_fma_f32 v[106:107], v[104:105], v[106:107], s[46:47] op_sel_hi:[1,1,0]
	s_nop 0
	v_pk_mul_f32 v[104:105], v[104:105], v[106:107]
	v_pk_mul_f32 v[106:107], v[86:87], v[86:87]
	s_nop 0
	v_pk_mul_f32 v[106:107], v[106:107], s[62:63] op_sel_hi:[1,0]
	s_nop 0
	v_exp_f32_e32 v106, v106
	v_exp_f32_e32 v107, v107
	s_nop 0
	v_pk_mul_f32 v[104:105], v[106:107], v[104:105]
	s_nop 0
	v_pk_mul_f32 v[106:107], v[86:87], v[104:105]
	v_pk_fma_f32 v[104:105], v[86:87], v[104:105], v[86:87] neg_lo:[1,0,0] neg_hi:[1,0,0]
	s_nop 0
	v_cndmask_b32_e64 v87, v105, v107, s[0:1]
	v_cndmask_b32_e32 v86, v104, v106, vcc
	v_lshlrev_b32_e32 v106, 16, v119
	v_and_b32_e32 v107, 0xffff0000, v119
	v_pk_fma_f32 v[68:69], v[22:23], v[106:107], v[68:69]
	v_pk_mul_f32 v[126:127], v[90:91], v[86:87]
	v_and_b32_e32 v87, 0x7fffffff, v69
	v_and_b32_e32 v86, 0x7fffffff, v68
	v_pk_fma_f32 v[86:87], v[86:87], s[10:11], 1.0 op_sel_hi:[1,0,0]
	v_lshlrev_b32_e32 v104, 16, v123
	v_rcp_f32_e32 v86, v86
	v_rcp_f32_e32 v87, v87
	v_and_b32_e32 v105, 0xffff0000, v123
	v_cmp_gt_f32_e32 vcc, 0, v68
	v_cmp_gt_f32_e64 s[0:1], 0, v69
	v_pk_fma_f32 v[90:91], v[86:87], s[56:57], v[98:99] op_sel_hi:[1,0,0]
	v_pk_fma_f32 v[72:73], v[54:55], v[104:105], v[72:73]
	v_pk_fma_f32 v[90:91], v[86:87], v[90:91], s[58:59] op_sel_hi:[1,1,0]
	v_pk_fma_f32 v[80:81], v[14:15], v[106:107], v[80:81]
	v_pk_fma_f32 v[90:91], v[86:87], v[90:91], s[20:21] op_sel_hi:[1,1,0]
	v_pk_fma_f32 v[76:77], v[46:47], v[104:105], v[76:77]
	v_pk_fma_f32 v[90:91], v[86:87], v[90:91], s[46:47] op_sel_hi:[1,1,0]
	v_pk_fma_f32 v[106:107], v[10:11], v[106:107], v[34:35]
	v_pk_mul_f32 v[86:87], v[86:87], v[90:91]
	v_pk_mul_f32 v[90:91], v[68:69], v[68:69]
	v_pk_fma_f32 v[104:105], v[38:39], v[104:105], v[62:63]
	v_pk_mul_f32 v[90:91], v[90:91], s[62:63] op_sel_hi:[1,0]
	s_nop 0
	v_exp_f32_e32 v90, v90
	v_exp_f32_e32 v91, v91
	s_nop 0
	v_pk_mul_f32 v[86:87], v[90:91], v[86:87]
	s_nop 0
	v_pk_mul_f32 v[90:91], v[68:69], v[86:87]
	v_pk_fma_f32 v[86:87], v[68:69], v[86:87], v[68:69] neg_lo:[1,0,0] neg_hi:[1,0,0]
	s_nop 0
	v_cndmask_b32_e64 v69, v87, v91, s[0:1]
	v_cndmask_b32_e32 v68, v86, v90, vcc
	v_pk_mul_f32 v[72:73], v[72:73], v[68:69]
	v_pk_fma_f32 v[68:69], v[4:5], v[84:85], v[28:29]
	v_lshlrev_b32_e32 v90, 16, v120
	v_pk_fma_f32 v[68:69], v[16:17], v[114:115], v[68:69]
	v_and_b32_e32 v91, 0xffff0000, v120
	v_pk_fma_f32 v[68:69], v[24:25], v[90:91], v[68:69]
	v_pk_fma_f32 v[84:85], v[40:41], v[88:89], v[64:65]
	v_and_b32_e32 v87, 0x7fffffff, v69
	v_and_b32_e32 v86, 0x7fffffff, v68
	v_pk_fma_f32 v[86:87], v[86:87], s[10:11], 1.0 op_sel_hi:[1,0,0]
	v_pk_fma_f32 v[84:85], v[48:49], v[116:117], v[84:85]
	v_rcp_f32_e32 v86, v86
	v_rcp_f32_e32 v87, v87
	v_lshlrev_b32_e32 v88, 16, v124
	v_and_b32_e32 v89, 0xffff0000, v124
	v_cmp_gt_f32_e32 vcc, 0, v68
	v_pk_fma_f32 v[118:119], v[86:87], s[56:57], v[98:99] op_sel_hi:[1,0,0]
	v_cmp_gt_f32_e64 s[0:1], 0, v69
	v_pk_fma_f32 v[118:119], v[86:87], v[118:119], s[58:59] op_sel_hi:[1,1,0]
	v_pk_fma_f32 v[84:85], v[56:57], v[88:89], v[84:85]
	v_pk_fma_f32 v[118:119], v[86:87], v[118:119], s[20:21] op_sel_hi:[1,1,0]
	s_nop 0
	v_pk_fma_f32 v[118:119], v[86:87], v[118:119], s[46:47] op_sel_hi:[1,1,0]
	s_nop 0
	v_pk_mul_f32 v[86:87], v[86:87], v[118:119]
	v_pk_mul_f32 v[118:119], v[68:69], v[68:69]
	s_nop 0
	v_pk_mul_f32 v[118:119], v[118:119], s[62:63] op_sel_hi:[1,0]
	s_nop 0
	v_exp_f32_e32 v118, v118
	v_exp_f32_e32 v119, v119
	s_nop 0
	v_pk_mul_f32 v[86:87], v[118:119], v[86:87]
	s_nop 0
	v_pk_mul_f32 v[118:119], v[68:69], v[86:87]
	v_pk_fma_f32 v[86:87], v[68:69], v[86:87], v[68:69] neg_lo:[1,0,0] neg_hi:[1,0,0]
	s_nop 0
	v_cndmask_b32_e64 v69, v87, v119, s[0:1]
	v_cndmask_b32_e32 v68, v86, v118, vcc
	v_pk_mul_f32 v[118:119], v[84:85], v[68:69]
	v_pk_fma_f32 v[68:69], v[6:7], v[70:71], v[30:31]
	v_lshlrev_b32_e32 v86, 16, v121
	v_pk_fma_f32 v[68:69], v[18:19], v[82:83], v[68:69]
	v_and_b32_e32 v87, 0xffff0000, v121
	v_pk_fma_f32 v[68:69], v[26:27], v[86:87], v[68:69]
	v_pk_fma_f32 v[70:71], v[42:43], v[74:75], v[66:67]
	v_and_b32_e32 v75, 0x7fffffff, v69
	v_and_b32_e32 v74, 0x7fffffff, v68
	v_pk_fma_f32 v[74:75], v[74:75], s[10:11], 1.0 op_sel_hi:[1,0,0]
	v_pk_fma_f32 v[70:71], v[50:51], v[78:79], v[70:71]
	v_rcp_f32_e32 v74, v74
	v_rcp_f32_e32 v75, v75
	v_lshlrev_b32_e32 v84, 16, v125
	v_and_b32_e32 v85, 0xffff0000, v125
	v_cmp_gt_f32_e32 vcc, 0, v68
	v_pk_fma_f32 v[120:121], v[74:75], s[56:57], v[98:99] op_sel_hi:[1,0,0]
	v_cmp_gt_f32_e64 s[0:1], 0, v69
	v_pk_fma_f32 v[120:121], v[74:75], v[120:121], s[58:59] op_sel_hi:[1,1,0]
	v_pk_fma_f32 v[70:71], v[58:59], v[84:85], v[70:71]
	v_pk_fma_f32 v[120:121], v[74:75], v[120:121], s[20:21] op_sel_hi:[1,1,0]
	v_pk_fma_f32 v[78:79], v[42:43], v[78:79], v[66:67]
	v_pk_fma_f32 v[120:121], v[74:75], v[120:121], s[46:47] op_sel_hi:[1,1,0]
	v_pk_fma_f32 v[78:79], v[50:51], v[84:85], v[78:79]
	v_pk_mul_f32 v[74:75], v[74:75], v[120:121]
	v_pk_mul_f32 v[120:121], v[68:69], v[68:69]
	v_pk_fma_f32 v[84:85], v[42:43], v[84:85], v[66:67]
	v_pk_mul_f32 v[120:121], v[120:121], s[62:63] op_sel_hi:[1,0]
	s_nop 0
	v_exp_f32_e32 v120, v120
	v_exp_f32_e32 v121, v121
	s_nop 0
	v_pk_mul_f32 v[74:75], v[120:121], v[74:75]
	s_nop 0
	v_pk_mul_f32 v[120:121], v[68:69], v[74:75]
	v_pk_fma_f32 v[74:75], v[68:69], v[74:75], v[68:69] neg_lo:[1,0,0] neg_hi:[1,0,0]
	s_nop 0
	v_cndmask_b32_e64 v69, v75, v121, s[0:1]
	v_cndmask_b32_e32 v68, v74, v120, vcc
	v_pk_mul_f32 v[74:75], v[70:71], v[68:69]
	s_mov_b64 s[0:1], s[54:55]
	v_cvt_pk_bf16_f32 v69, v72, v73
	v_cvt_pk_bf16_f32 v71, v74, v75
	v_add_u32_e32 v74, -2, v0
	v_mov_b64_e32 v[72:73], s[0:1]
	v_mad_i64_i32 v[72:73], s[0:1], v74, s59, v[72:73]
	v_lshl_add_u64 v[72:73], v[72:73], 0, v[2:3]
	v_add_co_u32_e32 v72, vcc, s73, v72
	v_cvt_pk_bf16_f32 v68, v126, v127
	v_cvt_pk_bf16_f32 v70, v118, v119
	v_addc_co_u32_e32 v73, vcc, 0, v73, vcc
	s_mov_b32 s0, 0x198aa000
	global_store_dwordx4 v[72:73], v[68:71], off offset:512
	s_nop 1
	v_add_co_u32_e32 v68, vcc, s0, v100
	s_mov_b32 s0, 0x198ad000
	s_nop 0
	v_addc_co_u32_e32 v69, vcc, 0, v101, vcc
	global_load_dwordx4 v[68:71], v[68:69], off offset:3584
	v_add_co_u32_e32 v72, vcc, s0, v100
	s_nop 1
	v_addc_co_u32_e32 v73, vcc, 0, v101, vcc
	global_load_dwordx4 v[72:75], v[72:73], off offset:2304
	s_waitcnt vmcnt(1)
	v_lshlrev_b32_e32 v126, 16, v68
	v_and_b32_e32 v127, 0xffff0000, v68
	v_pk_fma_f32 v[102:103], v[20:21], v[126:127], v[102:103]
	v_lshlrev_b32_e32 v122, 16, v69
	v_and_b32_e32 v119, 0x7fffffff, v103
	v_and_b32_e32 v118, 0x7fffffff, v102
	v_pk_fma_f32 v[118:119], v[118:119], s[10:11], 1.0 op_sel_hi:[1,0,0]
	s_waitcnt vmcnt(0)
	v_lshlrev_b32_e32 v124, 16, v72
	v_rcp_f32_e32 v118, v118
	v_rcp_f32_e32 v119, v119
	v_and_b32_e32 v125, 0xffff0000, v72
	v_cmp_gt_f32_e32 vcc, 0, v102
	v_cmp_gt_f32_e64 s[0:1], 0, v103
	v_pk_fma_f32 v[120:121], v[118:119], s[56:57], v[98:99] op_sel_hi:[1,0,0]
	v_and_b32_e32 v123, 0xffff0000, v69
	v_pk_fma_f32 v[120:121], v[118:119], v[120:121], s[58:59] op_sel_hi:[1,1,0]
	v_pk_fma_f32 v[112:113], v[52:53], v[124:125], v[112:113]
	v_pk_fma_f32 v[120:121], v[118:119], v[120:121], s[20:21] op_sel_hi:[1,1,0]
	v_pk_fma_f32 v[80:81], v[22:23], v[122:123], v[80:81]
	v_pk_fma_f32 v[120:121], v[118:119], v[120:121], s[46:47] op_sel_hi:[1,1,0]
	v_pk_fma_f32 v[108:109], v[44:45], v[124:125], v[108:109]
	v_pk_mul_f32 v[118:119], v[118:119], v[120:121]
	v_pk_mul_f32 v[120:121], v[102:103], v[102:103]
	v_pk_fma_f32 v[106:107], v[14:15], v[122:123], v[106:107]
	v_pk_mul_f32 v[120:121], v[120:121], s[62:63] op_sel_hi:[1,0]
	s_nop 0
	v_exp_f32_e32 v120, v120
	v_exp_f32_e32 v121, v121
	s_nop 0
	v_pk_mul_f32 v[118:119], v[120:121], v[118:119]
	s_nop 0
	v_pk_mul_f32 v[120:121], v[102:103], v[118:119]
	v_pk_fma_f32 v[118:119], v[102:103], v[118:119], v[102:103] neg_lo:[1,0,0] neg_hi:[1,0,0]
	s_nop 0
	v_cndmask_b32_e64 v103, v119, v121, s[0:1]
	v_cndmask_b32_e32 v102, v118, v120, vcc
	v_pk_mul_f32 v[130:131], v[112:113], v[102:103]
	v_and_b32_e32 v103, 0x7fffffff, v81
	v_and_b32_e32 v102, 0x7fffffff, v80
	v_pk_fma_f32 v[102:103], v[102:103], s[10:11], 1.0 op_sel_hi:[1,0,0]
	v_lshlrev_b32_e32 v120, 16, v73
	v_rcp_f32_e32 v102, v102
	v_rcp_f32_e32 v103, v103
	v_and_b32_e32 v121, 0xffff0000, v73
	v_cmp_gt_f32_e32 vcc, 0, v80
	v_cmp_gt_f32_e64 s[0:1], 0, v81
	v_pk_fma_f32 v[112:113], v[102:103], s[56:57], v[98:99] op_sel_hi:[1,0,0]
	v_pk_fma_f32 v[76:77], v[54:55], v[120:121], v[76:77]
	v_pk_fma_f32 v[112:113], v[102:103], v[112:113], s[58:59] op_sel_hi:[1,1,0]
	v_lshlrev_b32_e32 v118, 16, v70
	v_pk_fma_f32 v[112:113], v[102:103], v[112:113], s[20:21] op_sel_hi:[1,1,0]
	v_and_b32_e32 v119, 0xffff0000, v70
	v_pk_fma_f32 v[112:113], v[102:103], v[112:113], s[46:47] op_sel_hi:[1,1,0]
	v_pk_fma_f32 v[104:105], v[46:47], v[120:121], v[104:105]
	v_pk_mul_f32 v[102:103], v[102:103], v[112:113]
	v_pk_mul_f32 v[112:113], v[80:81], v[80:81]
	s_nop 0
	v_pk_mul_f32 v[112:113], v[112:113], s[62:63] op_sel_hi:[1,0]
	s_nop 0
	v_exp_f32_e32 v112, v112
	v_exp_f32_e32 v113, v113
	s_nop 0
	v_pk_mul_f32 v[102:103], v[112:113], v[102:103]
	s_nop 0
	v_pk_mul_f32 v[112:113], v[80:81], v[102:103]
	v_pk_fma_f32 v[102:103], v[80:81], v[102:103], v[80:81] neg_lo:[1,0,0] neg_hi:[1,0,0]
	s_nop 0
	v_cndmask_b32_e64 v81, v103, v113, s[0:1]
	v_cndmask_b32_e32 v80, v102, v112, vcc
	v_pk_mul_f32 v[80:81], v[76:77], v[80:81]
	v_pk_fma_f32 v[76:77], v[4:5], v[114:115], v[28:29]
	v_pk_fma_f32 v[102:103], v[40:41], v[116:117], v[64:65]
	v_pk_fma_f32 v[76:77], v[16:17], v[90:91], v[76:77]
	v_pk_fma_f32 v[102:103], v[48:49], v[88:89], v[102:103]
	v_pk_fma_f32 v[76:77], v[24:25], v[118:119], v[76:77]
	v_lshlrev_b32_e32 v114, 16, v74
	v_and_b32_e32 v113, 0x7fffffff, v77
	v_and_b32_e32 v112, 0x7fffffff, v76
	v_pk_fma_f32 v[112:113], v[112:113], s[10:11], 1.0 op_sel_hi:[1,0,0]
	v_and_b32_e32 v115, 0xffff0000, v74
	v_rcp_f32_e32 v112, v112
	v_rcp_f32_e32 v113, v113
	v_cmp_gt_f32_e32 vcc, 0, v76
	v_cmp_gt_f32_e64 s[0:1], 0, v77
	v_pk_fma_f32 v[102:103], v[56:57], v[114:115], v[102:103]
	v_pk_fma_f32 v[116:117], v[112:113], s[56:57], v[98:99] op_sel_hi:[1,0,0]
	v_pk_fma_f32 v[90:91], v[4:5], v[90:91], v[28:29]
	v_pk_fma_f32 v[116:117], v[112:113], v[116:117], s[58:59] op_sel_hi:[1,1,0]
	v_pk_fma_f32 v[90:91], v[16:17], v[118:119], v[90:91]
	v_pk_fma_f32 v[116:117], v[112:113], v[116:117], s[20:21] op_sel_hi:[1,1,0]
	v_pk_fma_f32 v[88:89], v[40:41], v[88:89], v[64:65]
	v_pk_fma_f32 v[116:117], v[112:113], v[116:117], s[46:47] op_sel_hi:[1,1,0]
	v_pk_fma_f32 v[88:89], v[48:49], v[114:115], v[88:89]
	v_pk_mul_f32 v[112:113], v[112:113], v[116:117]
	v_pk_mul_f32 v[116:117], v[76:77], v[76:77]
	s_nop 0
	v_pk_mul_f32 v[116:117], v[116:117], s[62:63] op_sel_hi:[1,0]
	s_nop 0
	v_exp_f32_e32 v116, v116
	v_exp_f32_e32 v117, v117
	s_nop 0
	v_pk_mul_f32 v[112:113], v[116:117], v[112:113]
	s_nop 0
	v_pk_mul_f32 v[116:117], v[76:77], v[112:113]
	v_pk_fma_f32 v[112:113], v[76:77], v[112:113], v[76:77] neg_lo:[1,0,0] neg_hi:[1,0,0]
	s_nop 0
	v_cndmask_b32_e64 v77, v113, v117, s[0:1]
	v_cndmask_b32_e32 v76, v112, v116, vcc
	v_pk_mul_f32 v[116:117], v[102:103], v[76:77]
	v_pk_fma_f32 v[76:77], v[6:7], v[82:83], v[30:31]
	v_lshlrev_b32_e32 v112, 16, v71
	v_pk_fma_f32 v[76:77], v[18:19], v[86:87], v[76:77]
	v_and_b32_e32 v113, 0xffff0000, v71
	v_pk_fma_f32 v[76:77], v[26:27], v[112:113], v[76:77]
	v_lshlrev_b32_e32 v102, 16, v75
	v_and_b32_e32 v83, 0x7fffffff, v77
	v_and_b32_e32 v82, 0x7fffffff, v76
	v_pk_fma_f32 v[82:83], v[82:83], s[10:11], 1.0 op_sel_hi:[1,0,0]
	v_and_b32_e32 v103, 0xffff0000, v75
	v_rcp_f32_e32 v82, v82
	v_rcp_f32_e32 v83, v83
	v_cmp_gt_f32_e32 vcc, 0, v76
	v_cmp_gt_f32_e64 s[0:1], 0, v77
	v_pk_fma_f32 v[78:79], v[58:59], v[102:103], v[78:79]
	v_pk_fma_f32 v[132:133], v[82:83], s[56:57], v[98:99] op_sel_hi:[1,0,0]
	v_pk_fma_f32 v[86:87], v[6:7], v[86:87], v[30:31]
	v_pk_fma_f32 v[132:133], v[82:83], v[132:133], s[58:59] op_sel_hi:[1,1,0]
	v_pk_fma_f32 v[86:87], v[18:19], v[112:113], v[86:87]
	v_pk_fma_f32 v[132:133], v[82:83], v[132:133], s[20:21] op_sel_hi:[1,1,0]
	v_pk_fma_f32 v[84:85], v[50:51], v[102:103], v[84:85]
	v_pk_fma_f32 v[132:133], v[82:83], v[132:133], s[46:47] op_sel_hi:[1,1,0]
	s_nop 0
	v_pk_mul_f32 v[82:83], v[82:83], v[132:133]
	v_pk_mul_f32 v[132:133], v[76:77], v[76:77]
	s_nop 0
	v_pk_mul_f32 v[132:133], v[132:133], s[62:63] op_sel_hi:[1,0]
	s_nop 0
	v_exp_f32_e32 v132, v132
	v_exp_f32_e32 v133, v133
	s_nop 0
	v_pk_mul_f32 v[82:83], v[132:133], v[82:83]
	s_nop 0
	v_pk_mul_f32 v[132:133], v[76:77], v[82:83]
	v_pk_fma_f32 v[82:83], v[76:77], v[82:83], v[76:77] neg_lo:[1,0,0] neg_hi:[1,0,0]
	s_nop 0
	v_cndmask_b32_e64 v77, v83, v133, s[0:1]
	v_cndmask_b32_e32 v76, v82, v132, vcc
	v_pk_mul_f32 v[82:83], v[78:79], v[76:77]
	s_mov_b64 s[0:1], s[54:55]
	v_cvt_pk_bf16_f32 v77, v80, v81
	v_cvt_pk_bf16_f32 v79, v82, v83
	v_add_u32_e32 v82, -1, v0
	v_mov_b64_e32 v[80:81], s[0:1]
	v_mad_i64_i32 v[80:81], s[0:1], v82, s59, v[80:81]
	v_lshl_add_u64 v[80:81], v[80:81], 0, v[2:3]
	v_add_co_u32_e32 v80, vcc, s73, v80
	v_cvt_pk_bf16_f32 v76, v130, v131
	v_cvt_pk_bf16_f32 v78, v116, v117
	v_addc_co_u32_e32 v81, vcc, 0, v81, vcc
	s_mov_b32 s0, 0x198b0000
	global_store_dwordx4 v[80:81], v[76:79], off offset:512
	s_nop 1
	v_add_co_u32_e32 v76, vcc, s0, v100
	s_mov_b32 s0, 0x198b2000
	s_nop 0
	v_addc_co_u32_e32 v77, vcc, 0, v101, vcc
	global_load_dwordx4 v[80:83], v[76:77], off offset:1024
	v_add_co_u32_e32 v76, vcc, s0, v100
	s_nop 1
	v_addc_co_u32_e32 v77, vcc, 0, v101, vcc
	global_load_dwordx4 v[76:79], v[76:77], off offset:3840
	v_pk_fma_f32 v[100:101], v[8:9], v[110:111], v[32:33]
	s_waitcnt vmcnt(1)
	v_lshlrev_b32_e32 v110, 16, v80
	v_pk_fma_f32 v[100:101], v[12:13], v[126:127], v[100:101]
	v_and_b32_e32 v111, 0xffff0000, v80
	v_pk_fma_f32 v[100:101], v[20:21], v[110:111], v[100:101]
	s_waitcnt vmcnt(0)
	v_lshlrev_b32_e32 v110, 16, v76
	v_and_b32_e32 v111, 0xffff0000, v76
	v_pk_fma_f32 v[108:109], v[52:53], v[110:111], v[108:109]
	v_and_b32_e32 v111, 0x7fffffff, v101
	v_and_b32_e32 v110, 0x7fffffff, v100
	v_pk_fma_f32 v[110:111], v[110:111], s[10:11], 1.0 op_sel_hi:[1,0,0]
	v_cmp_gt_f32_e32 vcc, 0, v100
	v_rcp_f32_e32 v110, v110
	v_rcp_f32_e32 v111, v111
	v_cmp_gt_f32_e64 s[0:1], 0, v101
	v_pk_fma_f32 v[116:117], v[110:111], s[56:57], v[98:99] op_sel_hi:[1,0,0]
	s_nop 0
	v_pk_fma_f32 v[116:117], v[110:111], v[116:117], s[58:59] op_sel_hi:[1,1,0]
	s_nop 0
	v_pk_fma_f32 v[116:117], v[110:111], v[116:117], s[20:21] op_sel_hi:[1,1,0]
	s_nop 0
	v_pk_fma_f32 v[116:117], v[110:111], v[116:117], s[46:47] op_sel_hi:[1,1,0]
	s_nop 0
	v_pk_mul_f32 v[110:111], v[110:111], v[116:117]
	v_pk_mul_f32 v[116:117], v[100:101], v[100:101]
	s_nop 0
	v_pk_mul_f32 v[116:117], v[116:117], s[62:63] op_sel_hi:[1,0]
	s_nop 0
	v_exp_f32_e32 v116, v116
	v_exp_f32_e32 v117, v117
	s_nop 0
	v_pk_mul_f32 v[110:111], v[116:117], v[110:111]
	s_nop 0
	v_pk_mul_f32 v[116:117], v[100:101], v[110:111]
	v_pk_fma_f32 v[110:111], v[100:101], v[110:111], v[100:101] neg_lo:[1,0,0] neg_hi:[1,0,0]
	s_nop 0
	v_cndmask_b32_e64 v101, v111, v117, s[0:1]
	v_cndmask_b32_e32 v100, v110, v116, vcc
	v_pk_mul_f32 v[100:101], v[108:109], v[100:101]
	v_lshlrev_b32_e32 v108, 16, v81
	v_and_b32_e32 v109, 0xffff0000, v81
	v_pk_fma_f32 v[106:107], v[22:23], v[108:109], v[106:107]
	v_lshlrev_b32_e32 v108, 16, v77
	v_and_b32_e32 v109, 0xffff0000, v77
	v_pk_fma_f32 v[104:105], v[54:55], v[108:109], v[104:105]
	v_and_b32_e32 v109, 0x7fffffff, v107
	v_and_b32_e32 v108, 0x7fffffff, v106
	v_pk_fma_f32 v[108:109], v[108:109], s[10:11], 1.0 op_sel_hi:[1,0,0]
	v_cmp_gt_f32_e32 vcc, 0, v106
	v_rcp_f32_e32 v108, v108
	v_rcp_f32_e32 v109, v109
	v_cmp_gt_f32_e64 s[0:1], 0, v107
	v_pk_fma_f32 v[110:111], v[108:109], s[56:57], v[98:99] op_sel_hi:[1,0,0]
	s_nop 0
	v_pk_fma_f32 v[110:111], v[108:109], v[110:111], s[58:59] op_sel_hi:[1,1,0]
	s_nop 0
	v_pk_fma_f32 v[110:111], v[108:109], v[110:111], s[20:21] op_sel_hi:[1,1,0]
	s_nop 0
	v_pk_fma_f32 v[110:111], v[108:109], v[110:111], s[46:47] op_sel_hi:[1,1,0]
	s_nop 0
	v_pk_mul_f32 v[108:109], v[108:109], v[110:111]
	v_pk_mul_f32 v[110:111], v[106:107], v[106:107]
	s_nop 0
	v_pk_mul_f32 v[110:111], v[110:111], s[62:63] op_sel_hi:[1,0]
	s_nop 0
	v_exp_f32_e32 v110, v110
	v_exp_f32_e32 v111, v111
	s_nop 0
	v_pk_mul_f32 v[108:109], v[110:111], v[108:109]
	s_nop 0
	v_pk_mul_f32 v[110:111], v[106:107], v[108:109]
	v_pk_fma_f32 v[108:109], v[106:107], v[108:109], v[106:107] neg_lo:[1,0,0] neg_hi:[1,0,0]
	s_nop 0
	v_cndmask_b32_e64 v107, v109, v111, s[0:1]
	v_cndmask_b32_e32 v106, v108, v110, vcc
	v_pk_mul_f32 v[104:105], v[104:105], v[106:107]
	v_lshlrev_b32_e32 v106, 16, v82
	v_and_b32_e32 v107, 0xffff0000, v82
	v_pk_fma_f32 v[90:91], v[24:25], v[106:107], v[90:91]
	v_lshlrev_b32_e32 v106, 16, v78
	v_and_b32_e32 v107, 0xffff0000, v78
	v_pk_fma_f32 v[88:89], v[56:57], v[106:107], v[88:89]
	v_and_b32_e32 v107, 0x7fffffff, v91
	v_and_b32_e32 v106, 0x7fffffff, v90
	v_pk_fma_f32 v[106:107], v[106:107], s[10:11], 1.0 op_sel_hi:[1,0,0]
	v_cmp_gt_f32_e32 vcc, 0, v90
	v_rcp_f32_e32 v106, v106
	v_rcp_f32_e32 v107, v107
	v_cmp_gt_f32_e64 s[0:1], 0, v91
	v_pk_fma_f32 v[108:109], v[106:107], s[56:57], v[98:99] op_sel_hi:[1,0,0]
	s_nop 0
	v_pk_fma_f32 v[108:109], v[106:107], v[108:109], s[58:59] op_sel_hi:[1,1,0]
	s_nop 0
	v_pk_fma_f32 v[108:109], v[106:107], v[108:109], s[20:21] op_sel_hi:[1,1,0]
	s_nop 0
	v_pk_fma_f32 v[108:109], v[106:107], v[108:109], s[46:47] op_sel_hi:[1,1,0]
	s_nop 0
	v_pk_mul_f32 v[106:107], v[106:107], v[108:109]
	v_pk_mul_f32 v[108:109], v[90:91], v[90:91]
	s_nop 0
	v_pk_mul_f32 v[108:109], v[108:109], s[62:63] op_sel_hi:[1,0]
	s_nop 0
	v_exp_f32_e32 v108, v108
	v_exp_f32_e32 v109, v109
	s_nop 0
	v_pk_mul_f32 v[106:107], v[108:109], v[106:107]
	s_nop 0
	v_pk_mul_f32 v[108:109], v[90:91], v[106:107]
	v_pk_fma_f32 v[106:107], v[90:91], v[106:107], v[90:91] neg_lo:[1,0,0] neg_hi:[1,0,0]
	s_nop 0
	v_cndmask_b32_e64 v91, v107, v109, s[0:1]
	v_cndmask_b32_e32 v90, v106, v108, vcc
	v_pk_mul_f32 v[88:89], v[88:89], v[90:91]
	v_lshlrev_b32_e32 v90, 16, v83
	v_and_b32_e32 v91, 0xffff0000, v83
	v_pk_fma_f32 v[86:87], v[26:27], v[90:91], v[86:87]
	v_lshlrev_b32_e32 v90, 16, v79
	v_and_b32_e32 v91, 0xffff0000, v79
	v_pk_fma_f32 v[84:85], v[58:59], v[90:91], v[84:85]
	v_and_b32_e32 v91, 0x7fffffff, v87
	v_and_b32_e32 v90, 0x7fffffff, v86
	v_pk_fma_f32 v[90:91], v[90:91], s[10:11], 1.0 op_sel_hi:[1,0,0]
	v_cmp_gt_f32_e32 vcc, 0, v86
	v_rcp_f32_e32 v90, v90
	v_rcp_f32_e32 v91, v91
	v_cmp_gt_f32_e64 s[0:1], 0, v87
	v_pk_fma_f32 v[98:99], v[90:91], s[56:57], v[98:99] op_sel_hi:[1,0,0]
	s_nop 0
	v_pk_fma_f32 v[98:99], v[90:91], v[98:99], s[58:59] op_sel_hi:[1,1,0]
	s_nop 0
	v_pk_fma_f32 v[98:99], v[90:91], v[98:99], s[20:21] op_sel_hi:[1,1,0]
	s_nop 0
	v_pk_fma_f32 v[98:99], v[90:91], v[98:99], s[46:47] op_sel_hi:[1,1,0]
	s_nop 0
	v_pk_mul_f32 v[90:91], v[90:91], v[98:99]
	v_pk_mul_f32 v[98:99], v[86:87], v[86:87]
	s_nop 0
	v_pk_mul_f32 v[98:99], v[98:99], s[62:63] op_sel_hi:[1,0]
	s_nop 0
	v_exp_f32_e32 v98, v98
	v_exp_f32_e32 v99, v99
	s_nop 0
	v_pk_mul_f32 v[90:91], v[98:99], v[90:91]
	s_nop 0
	v_pk_mul_f32 v[98:99], v[86:87], v[90:91]
	v_pk_fma_f32 v[90:91], v[86:87], v[90:91], v[86:87] neg_lo:[1,0,0] neg_hi:[1,0,0]
	s_nop 0
	v_cndmask_b32_e64 v87, v91, v99, s[0:1]
	v_cndmask_b32_e32 v86, v90, v98, vcc
	s_mov_b64 s[0:1], s[54:55]
	v_pk_mul_f32 v[90:91], v[84:85], v[86:87]
	v_cvt_pk_bf16_f32 v86, v88, v89
	v_cvt_pk_bf16_f32 v84, v100, v101
	v_mov_b64_e32 v[88:89], s[0:1]
	v_mad_i64_i32 v[88:89], s[0:1], v0, s59, v[88:89]
	v_lshl_add_u64 v[88:89], v[88:89], 0, v[2:3]
	v_add_co_u32_e32 v88, vcc, s73, v88
	v_cvt_pk_bf16_f32 v85, v104, v105
	v_cvt_pk_bf16_f32 v87, v90, v91
	v_addc_co_u32_e32 v89, vcc, 0, v89, vcc
	v_add_u32_e32 v0, 4, v0
	global_store_dwordx4 v[88:89], v[84:87], off offset:512
	s_cbranch_scc0 .LBB0_1011
	v_subrev_u32_e32 v128, s40, v128
	s_mov_b32 s0, 0x56abf
	v_cmp_gt_i32_e32 vcc, 0, v128
	s_or_b64 s[26:27], vcc, s[26:27]
	s_andn2_b64 exec, exec, s[26:27]
	s_cbranch_execnz .LBB0_1006
